# SWA (layer 1) tile loop: QK with all K fragments read up front, 16-instr max tree, exp/cvt interleaved with PV MFMAs
# speedup vs baseline: 1.0125x; 1.0125x over previous
.LBB0_251:
	s_and_b32 s10, s31, 0x4000
	v_add3_u32 v94, s10, v108, v107
	v_add3_u32 v95, s10, v109, v107
	v_add3_u32 v117, s10, v110, v107
	v_add3_u32 v118, s10, v111, v107
	ds_read_b128 v[148:151], v94
	ds_read_b128 v[152:155], v95
	ds_read_b128 v[156:159], v117
	ds_read_b128 v[160:163], v118
	ds_read_b128 v[164:167], v94 offset:4096
	ds_read_b128 v[168:171], v95 offset:4096
	ds_read_b128 v[172:175], v117 offset:4096
	ds_read_b128 v[176:179], v118 offset:4096
	s_andn2_b64 vcc, exec, s[40:41]
	s_waitcnt lgkmcnt(7)
	v_mfma_f32_32x32x16_bf16 v[48:63], v[148:151], v[2:5], 0
	s_waitcnt lgkmcnt(6)
	v_mfma_f32_32x32x16_bf16 v[48:63], v[152:155], v[6:9], v[48:63]
	s_waitcnt lgkmcnt(5)
	v_mfma_f32_32x32x16_bf16 v[48:63], v[156:159], v[10:13], v[48:63]
	s_waitcnt lgkmcnt(4)
	v_mfma_f32_32x32x16_bf16 v[48:63], v[160:163], v[80:83], v[48:63]
	s_waitcnt lgkmcnt(3)
	v_mfma_f32_32x32x16_bf16 v[64:79], v[164:167], v[2:5], 0
	s_waitcnt lgkmcnt(2)
	v_mfma_f32_32x32x16_bf16 v[64:79], v[168:171], v[6:9], v[64:79]
	s_waitcnt lgkmcnt(1)
	v_mfma_f32_32x32x16_bf16 v[64:79], v[172:175], v[10:13], v[64:79]
	s_waitcnt lgkmcnt(0)
	v_mfma_f32_32x32x16_bf16 v[64:79], v[176:179], v[80:83], v[64:79]
	s_cbranch_vccnz .LBB0_253
	v_add_u32_e32 v94, s29, v116
	v_add_u32_e32 v95, 0xfffffcff, v94
	s_movk_i32 s2, 0xfefe
	v_cmp_lt_u32_e32 vcc, s2, v95
	v_add_u32_e32 v95, 0xfffffd1f, v94
	s_nop 2
	v_cndmask_b32_e32 v48, v213, v48, vcc
	v_cmp_lt_u32_e32 vcc, s2, v95
	v_add_u32_e32 v95, 0xfffffd00, v94
	s_nop 0
	v_cndmask_b32_e32 v64, v213, v64, vcc
	v_cmp_lt_u32_e32 vcc, s2, v95
	v_add_u32_e32 v95, 0xfffffd20, v94
	s_nop 0
	v_cndmask_b32_e32 v49, v213, v49, vcc
	v_cmp_lt_u32_e32 vcc, s2, v95
	v_add_u32_e32 v95, 0xfffffd01, v94
	s_nop 0
	v_cndmask_b32_e32 v65, v213, v65, vcc
	v_cmp_lt_u32_e32 vcc, s2, v95
	v_add_u32_e32 v95, 0xfffffd21, v94
	s_nop 0
	v_cndmask_b32_e32 v50, v213, v50, vcc
	v_cmp_lt_u32_e32 vcc, s2, v95
	v_add_u32_e32 v95, 0xfffffd02, v94
	s_nop 0
	v_cndmask_b32_e32 v66, v213, v66, vcc
	v_cmp_lt_u32_e32 vcc, s2, v95
	v_add_u32_e32 v95, 0xfffffd22, v94
	s_nop 0
	v_cndmask_b32_e32 v51, v213, v51, vcc
	v_cmp_lt_u32_e32 vcc, s2, v95
	v_add_u32_e32 v95, 0xfffffd07, v94
	s_nop 0
	v_cndmask_b32_e32 v67, v213, v67, vcc
	v_cmp_lt_u32_e32 vcc, s2, v95
	v_add_u32_e32 v95, 0xfffffd27, v94
	s_nop 0
	v_cndmask_b32_e32 v52, v213, v52, vcc
	v_cmp_lt_u32_e32 vcc, s2, v95
	v_add_u32_e32 v95, 0xfffffd08, v94
	s_nop 0
	v_cndmask_b32_e32 v68, v213, v68, vcc
	v_cmp_lt_u32_e32 vcc, s2, v95
	v_add_u32_e32 v95, 0xfffffd28, v94
	s_nop 0
	v_cndmask_b32_e32 v53, v213, v53, vcc
	v_cmp_lt_u32_e32 vcc, s2, v95
	v_add_u32_e32 v95, 0xfffffd09, v94
	s_nop 0
	v_cndmask_b32_e32 v69, v213, v69, vcc
	v_cmp_lt_u32_e32 vcc, s2, v95
	v_add_u32_e32 v95, 0xfffffd29, v94
	s_nop 0
	v_cndmask_b32_e32 v54, v213, v54, vcc
	v_cmp_lt_u32_e32 vcc, s2, v95
	v_add_u32_e32 v95, 0xfffffd0a, v94
	s_nop 0
	v_cndmask_b32_e32 v70, v213, v70, vcc
	v_cmp_lt_u32_e32 vcc, s2, v95
	v_add_u32_e32 v95, 0xfffffd2a, v94
	s_nop 0
	v_cndmask_b32_e32 v55, v213, v55, vcc
	v_cmp_lt_u32_e32 vcc, s2, v95
	v_add_u32_e32 v95, 0xfffffd0f, v94
	s_nop 0
	v_cndmask_b32_e32 v71, v213, v71, vcc
	v_cmp_lt_u32_e32 vcc, s2, v95
	v_add_u32_e32 v95, 0xfffffd2f, v94
	s_nop 0
	v_cndmask_b32_e32 v56, v213, v56, vcc
	v_cmp_lt_u32_e32 vcc, s2, v95
	v_add_u32_e32 v95, 0xfffffd10, v94
	s_nop 0
	v_cndmask_b32_e32 v72, v213, v72, vcc
	v_cmp_lt_u32_e32 vcc, s2, v95
	v_add_u32_e32 v95, 0xfffffd30, v94
	s_nop 0
	v_cndmask_b32_e32 v57, v213, v57, vcc
	v_cmp_lt_u32_e32 vcc, s2, v95
	v_add_u32_e32 v95, 0xfffffd11, v94
	s_nop 0
	v_cndmask_b32_e32 v73, v213, v73, vcc
	v_cmp_lt_u32_e32 vcc, s2, v95
	v_add_u32_e32 v95, 0xfffffd31, v94
	s_nop 0
	v_cndmask_b32_e32 v58, v213, v58, vcc
	v_cmp_lt_u32_e32 vcc, s2, v95
	v_add_u32_e32 v95, 0xfffffd12, v94
	s_nop 0
	v_cndmask_b32_e32 v74, v213, v74, vcc
	v_cmp_lt_u32_e32 vcc, s2, v95
	v_add_u32_e32 v95, 0xfffffd32, v94
	s_nop 0
	v_cndmask_b32_e32 v59, v213, v59, vcc
	v_cmp_lt_u32_e32 vcc, s2, v95
	v_add_u32_e32 v95, 0xfffffd17, v94
	s_nop 0
	v_cndmask_b32_e32 v75, v213, v75, vcc
	v_cmp_lt_u32_e32 vcc, s2, v95
	v_add_u32_e32 v95, 0xfffffd37, v94
	s_nop 0
	v_cndmask_b32_e32 v60, v213, v60, vcc
	v_cmp_lt_u32_e32 vcc, s2, v95
	v_add_u32_e32 v95, 0xfffffd18, v94
	s_nop 0
	v_cndmask_b32_e32 v76, v213, v76, vcc
	v_cmp_lt_u32_e32 vcc, s2, v95
	v_add_u32_e32 v95, 0xfffffd38, v94
	s_nop 0
	v_cndmask_b32_e32 v61, v213, v61, vcc
	v_cmp_lt_u32_e32 vcc, s2, v95
	v_add_u32_e32 v95, 0xfffffd19, v94
	s_nop 0
	v_cndmask_b32_e32 v77, v213, v77, vcc
	v_cmp_lt_u32_e32 vcc, s2, v95
	v_add_u32_e32 v95, 0xfffffd39, v94
	v_add_u32_e32 v94, 0xfffffd1a, v94
	v_cndmask_b32_e32 v62, v213, v62, vcc
	v_cmp_lt_u32_e32 vcc, s2, v95
	s_nop 1
	v_cndmask_b32_e32 v78, v213, v78, vcc
	v_cmp_lt_u32_e32 vcc, s2, v94
	v_add_u32_e32 v94, s29, v115
	v_add_u32_e32 v94, 0xfffffd3a, v94
	v_cndmask_b32_e32 v63, v213, v63, vcc
	v_cmp_lt_u32_e32 vcc, s2, v94
	s_nop 1
	v_cndmask_b32_e32 v79, v213, v79, vcc
.LBB0_253:
	s_nop 10
	v_max3_f32 v94, v48, v49, v50
	v_max3_f32 v94, v94, v51, v52
	v_max3_f32 v94, v94, v53, v54
	v_max3_f32 v94, v94, v55, v56
	v_max3_f32 v94, v94, v57, v58
	v_max3_f32 v94, v94, v59, v60
	v_max3_f32 v94, v94, v61, v62
	v_max3_f32 v95, v64, v65, v66
	v_max3_f32 v95, v95, v67, v68
	v_max3_f32 v95, v95, v69, v70
	v_max3_f32 v95, v95, v71, v72
	v_max3_f32 v95, v95, v73, v74
	v_max3_f32 v95, v95, v75, v76
	v_max3_f32 v95, v95, v77, v78
	v_max3_f32 v94, v94, v95, v63
	v_max_f32_e32 v94, v94, v79
	v_mov_b32_e32 v95, v94
	s_nop 1
	v_permlane32_swap_b32_e32 v94, v95
	s_cmp_eq_u32 s45, 0
	v_max_f32_e32 v95, v95, v95
	v_max_f32_e32 v94, v94, v94
	s_cselect_b64 s[40:41], -1, 0
	v_max_f32_e32 v94, v94, v95
	s_and_b64 vcc, exec, s[40:41]
	s_cbranch_vccnz .LBB0_255
	v_sub_f32_e32 v95, v94, v104
	s_mov_b32 s2, 0x41000000
	v_cmp_ge_f32_e32 vcc, s2, v95
	s_cmp_lg_u64 vcc, exec
	s_cselect_b64 s[40:41], -1, 0

.LBB0_257:
	v_add3_u32 v94, s10, v112, v113
	v_add_u32_e32 v95, s10, v114
	ds_read_b64_tr_b16 v[148:149], v94 offset:8192
	ds_read_b64_tr_b16 v[150:151], v94 offset:9216
	ds_read_b64_tr_b16 v[152:153], v95 offset:8192
	ds_read_b64_tr_b16 v[154:155], v95 offset:9216
	ds_read_b64_tr_b16 v[156:157], v94 offset:10240
	ds_read_b64_tr_b16 v[158:159], v94 offset:11264
	ds_read_b64_tr_b16 v[160:161], v95 offset:10240
	ds_read_b64_tr_b16 v[162:163], v95 offset:11264
	ds_read_b64_tr_b16 v[164:165], v94 offset:12288
	ds_read_b64_tr_b16 v[166:167], v94 offset:13312
	ds_read_b64_tr_b16 v[168:169], v95 offset:12288
	ds_read_b64_tr_b16 v[170:171], v95 offset:13312
	v_sub_f32_e32 v48, v48, v104
	v_sub_f32_e32 v49, v49, v104
	v_sub_f32_e32 v50, v50, v104
	v_sub_f32_e32 v51, v51, v104
	v_sub_f32_e32 v52, v52, v104
	v_sub_f32_e32 v53, v53, v104
	v_sub_f32_e32 v54, v54, v104
	v_sub_f32_e32 v55, v55, v104
	v_exp_f32_e32 v48, v48
	v_exp_f32_e32 v49, v49
	v_exp_f32_e32 v50, v50
	v_exp_f32_e32 v51, v51
	v_exp_f32_e32 v52, v52
	v_exp_f32_e32 v53, v53
	v_exp_f32_e32 v54, v54
	v_exp_f32_e32 v55, v55
	v_cvt_pk_bf16_f32 v180, v48, v49
	v_cvt_pk_bf16_f32 v181, v50, v51
	v_cvt_pk_bf16_f32 v182, v52, v53
	v_cvt_pk_bf16_f32 v183, v54, v55
	v_add_f32_e32 v117, v48, v49
	v_add_f32_e32 v118, v50, v51
	v_add_f32_e32 v117, v117, v52
	v_add_f32_e32 v118, v118, v53
	v_add_f32_e32 v117, v117, v54
	v_add_f32_e32 v118, v118, v55
	v_add_f32_e32 v97, v97, v117
	v_add_f32_e32 v97, v97, v118
	s_waitcnt lgkmcnt(10)
	v_mfma_f32_32x32x16_bf16 v[16:31], v[148:151], v[180:183], v[16:31]
	s_waitcnt lgkmcnt(8)
	v_mfma_f32_32x32x16_bf16 v[32:47], v[152:155], v[180:183], v[32:47]
	ds_read_b64_tr_b16 v[172:173], v94 offset:14336
	ds_read_b64_tr_b16 v[174:175], v94 offset:15360
	ds_read_b64_tr_b16 v[176:177], v95 offset:14336
	ds_read_b64_tr_b16 v[178:179], v95 offset:15360
	v_sub_f32_e32 v56, v56, v104
	v_sub_f32_e32 v57, v57, v104
	v_sub_f32_e32 v58, v58, v104
	v_sub_f32_e32 v59, v59, v104
	v_sub_f32_e32 v60, v60, v104
	v_sub_f32_e32 v61, v61, v104
	v_sub_f32_e32 v62, v62, v104
	v_sub_f32_e32 v63, v63, v104
	v_exp_f32_e32 v56, v56
	v_exp_f32_e32 v57, v57
	v_exp_f32_e32 v58, v58
	v_exp_f32_e32 v59, v59
	v_exp_f32_e32 v60, v60
	v_exp_f32_e32 v61, v61
	v_exp_f32_e32 v62, v62
	v_exp_f32_e32 v63, v63
	v_cvt_pk_bf16_f32 v184, v56, v57
	v_cvt_pk_bf16_f32 v185, v58, v59
	v_cvt_pk_bf16_f32 v186, v60, v61
	v_cvt_pk_bf16_f32 v187, v62, v63
	v_add_f32_e32 v117, v56, v57
	v_add_f32_e32 v118, v58, v59
	v_add_f32_e32 v117, v117, v60
	v_add_f32_e32 v118, v118, v61
	v_add_f32_e32 v117, v117, v62
	v_add_f32_e32 v118, v118, v63
	v_add_f32_e32 v97, v97, v117
	v_add_f32_e32 v97, v97, v118
	s_waitcnt lgkmcnt(10)
	v_mfma_f32_32x32x16_bf16 v[16:31], v[156:159], v[184:187], v[16:31]
	s_waitcnt lgkmcnt(8)
	v_mfma_f32_32x32x16_bf16 v[32:47], v[160:163], v[184:187], v[32:47]
	v_sub_f32_e32 v64, v64, v104
	v_sub_f32_e32 v65, v65, v104
	v_sub_f32_e32 v66, v66, v104
	v_sub_f32_e32 v67, v67, v104
	v_sub_f32_e32 v68, v68, v104
	v_sub_f32_e32 v69, v69, v104
	v_sub_f32_e32 v70, v70, v104
	v_sub_f32_e32 v71, v71, v104
	v_exp_f32_e32 v64, v64
	v_exp_f32_e32 v65, v65
	v_exp_f32_e32 v66, v66
	v_exp_f32_e32 v67, v67
	v_exp_f32_e32 v68, v68
	v_exp_f32_e32 v69, v69
	v_exp_f32_e32 v70, v70
	v_exp_f32_e32 v71, v71
	v_cvt_pk_bf16_f32 v188, v64, v65
	v_cvt_pk_bf16_f32 v189, v66, v67
	v_cvt_pk_bf16_f32 v190, v68, v69
	v_cvt_pk_bf16_f32 v191, v70, v71
	v_add_f32_e32 v117, v64, v65
	v_add_f32_e32 v118, v66, v67
	v_add_f32_e32 v117, v117, v68
	v_add_f32_e32 v118, v118, v69
	v_add_f32_e32 v117, v117, v70
	v_add_f32_e32 v118, v118, v71
	v_add_f32_e32 v97, v97, v117
	v_add_f32_e32 v97, v97, v118
	s_waitcnt lgkmcnt(6)
	v_mfma_f32_32x32x16_bf16 v[16:31], v[164:167], v[188:191], v[16:31]
	s_waitcnt lgkmcnt(4)
	v_mfma_f32_32x32x16_bf16 v[32:47], v[168:171], v[188:191], v[32:47]
	v_sub_f32_e32 v72, v72, v104
	v_sub_f32_e32 v73, v73, v104
	v_sub_f32_e32 v74, v74, v104
	v_sub_f32_e32 v75, v75, v104
	v_sub_f32_e32 v76, v76, v104
	v_sub_f32_e32 v77, v77, v104
	v_sub_f32_e32 v78, v78, v104
	v_sub_f32_e32 v79, v79, v104
	v_exp_f32_e32 v72, v72
	v_exp_f32_e32 v73, v73
	v_exp_f32_e32 v74, v74
	v_exp_f32_e32 v75, v75
	v_exp_f32_e32 v76, v76
	v_exp_f32_e32 v77, v77
	v_exp_f32_e32 v78, v78
	v_exp_f32_e32 v79, v79
	v_cvt_pk_bf16_f32 v192, v72, v73
	v_cvt_pk_bf16_f32 v193, v74, v75
	v_cvt_pk_bf16_f32 v194, v76, v77
	v_cvt_pk_bf16_f32 v195, v78, v79
	v_add_f32_e32 v117, v72, v73
	v_add_f32_e32 v118, v74, v75
	v_add_f32_e32 v117, v117, v76
	v_add_f32_e32 v118, v118, v77
	v_add_f32_e32 v117, v117, v78
	v_add_f32_e32 v118, v118, v79
	v_add_f32_e32 v97, v97, v117
	v_add_f32_e32 v97, v97, v118
	s_waitcnt lgkmcnt(2)
	v_mfma_f32_32x32x16_bf16 v[16:31], v[172:175], v[192:195], v[16:31]
	s_waitcnt lgkmcnt(0)
	v_mfma_f32_32x32x16_bf16 v[32:47], v[176:179], v[192:195], v[32:47]
	s_andn2_b64 vcc, exec, s[38:39]
	s_mov_b64 s[10:11], -1
	s_cbranch_vccz .LBB0_249
